# MFMA Gray-code order: back-to-back accumulate pairs, consecutive MFMAs share accumulator or one operand (k-order alternates per pair; f32 sum order of the two K-halves swaps for half the accumulators)
# speedup vs baseline: 1.0199x; 1.0121x over previous
.LBB0_139:
	s_add_u32 s22, s18, 0xfff00080
	s_addc_u32 s23, s19, -1
	s_add_i32 s49, 0, 0x10000
	s_cmp_eq_u32 s48, 60
	s_cselect_b32 s25, s9, s23
	s_cselect_b32 s24, s44, s22
	s_cselect_b32 s23, s7, s47
	s_cselect_b32 s22, s45, s46
	s_add_i32 s52, 0, 0x14000
	v_add_u32_e32 v156, s49, v145
	v_add_u32_e32 v172, s52, v145
	ds_read_b128 v[140:143], v156
	ds_read_b128 v[148:151], v156 offset:1024
	ds_read_b128 v[152:155], v156 offset:2048
	ds_read_b128 v[156:159], v156 offset:3072
	ds_read_b128 v[160:163], v172
	ds_read_b128 v[164:167], v172 offset:1024
	ds_read_b128 v[168:171], v172 offset:2048
	ds_read_b128 v[190:193], v172 offset:3072
	v_lshl_add_u64 v[172:173], s[18:19], 0, v[136:137]
	s_add_i32 m0, s31, 0xc000
	ds_read_b128 v[194:197], v147
	ds_read_b128 v[198:201], v147 offset:1024
	ds_read_b128 v[202:205], v147 offset:2048
	ds_read_b128 v[206:209], v147 offset:3072
	ds_read_b128 v[228:231], v147 offset:4096
	ds_read_b128 v[232:235], v147 offset:5120
	ds_read_b128 v[236:239], v147 offset:6144
	ds_read_b128 v[240:243], v147 offset:7168
	global_load_lds_dwordx4 v[172:173], off
	v_lshl_add_u64 v[172:173], s[18:19], 0, v[138:139]
	s_add_i32 m0, s31, 0xe000
	s_nop 0
	global_load_lds_dwordx4 v[172:173], off
	s_waitcnt vmcnt(8)
	s_waitcnt lgkmcnt(0)
	s_barrier
	s_setprio 1
	s_waitcnt lgkmcnt(0)
	v_mfma_f32_16x16x32_bf16 v[126:129], v[140:143], v[194:197], v[126:129]
	v_mfma_f32_16x16x32_bf16 v[126:129], v[148:151], v[198:201], v[126:129]
	v_mfma_f32_16x16x32_bf16 v[122:125], v[156:159], v[198:201], v[122:125]
	v_mfma_f32_16x16x32_bf16 v[122:125], v[152:155], v[194:197], v[122:125]
	v_mfma_f32_16x16x32_bf16 v[110:113], v[152:155], v[202:205], v[110:113]
	v_mfma_f32_16x16x32_bf16 v[110:113], v[156:159], v[206:209], v[110:113]
	v_mfma_f32_16x16x32_bf16 v[118:121], v[148:151], v[206:209], v[118:121]
	v_mfma_f32_16x16x32_bf16 v[118:121], v[140:143], v[202:205], v[118:121]
	v_mfma_f32_16x16x32_bf16 v[102:105], v[140:143], v[228:231], v[102:105]
	v_mfma_f32_16x16x32_bf16 v[102:105], v[148:151], v[232:235], v[102:105]
	v_mfma_f32_16x16x32_bf16 v[94:97], v[156:159], v[232:235], v[94:97]
	v_mfma_f32_16x16x32_bf16 v[94:97], v[152:155], v[228:231], v[94:97]
	v_mfma_f32_16x16x32_bf16 v[78:81], v[152:155], v[236:239], v[78:81]
	v_mfma_f32_16x16x32_bf16 v[78:81], v[156:159], v[240:243], v[78:81]
	v_mfma_f32_16x16x32_bf16 v[86:89], v[148:151], v[240:243], v[86:89]
	v_mfma_f32_16x16x32_bf16 v[86:89], v[140:143], v[236:239], v[86:89]
	s_setprio 0
	s_setprio 1
	v_mfma_f32_16x16x32_bf16 v[114:117], v[160:163], v[194:197], v[114:117]
	v_mfma_f32_16x16x32_bf16 v[114:117], v[164:167], v[198:201], v[114:117]
	v_mfma_f32_16x16x32_bf16 v[106:109], v[190:193], v[198:201], v[106:109]
	v_mfma_f32_16x16x32_bf16 v[106:109], v[168:171], v[194:197], v[106:109]
	v_mfma_f32_16x16x32_bf16 v[90:93], v[168:171], v[202:205], v[90:93]
	v_mfma_f32_16x16x32_bf16 v[90:93], v[190:193], v[206:209], v[90:93]
	v_mfma_f32_16x16x32_bf16 v[98:101], v[164:167], v[206:209], v[98:101]
	v_mfma_f32_16x16x32_bf16 v[98:101], v[160:163], v[202:205], v[98:101]
	v_mfma_f32_16x16x32_bf16 v[82:85], v[160:163], v[228:231], v[82:85]
	v_mfma_f32_16x16x32_bf16 v[82:85], v[164:167], v[232:235], v[82:85]
	v_mfma_f32_16x16x32_bf16 v[74:77], v[190:193], v[232:235], v[74:77]
	v_mfma_f32_16x16x32_bf16 v[74:77], v[168:171], v[228:231], v[74:77]
	v_mfma_f32_16x16x32_bf16 v[66:69], v[168:171], v[236:239], v[66:69]
	v_mfma_f32_16x16x32_bf16 v[66:69], v[190:193], v[240:243], v[66:69]
	v_mfma_f32_16x16x32_bf16 v[70:73], v[164:167], v[240:243], v[70:73]
	v_mfma_f32_16x16x32_bf16 v[70:73], v[160:163], v[236:239], v[70:73]
	s_setprio 0
	s_barrier
	s_add_i32 s49, s49, s26
	v_lshl_add_u64 v[172:173], s[22:23], 0, v[0:1]
	s_mov_b32 m0, s49
	ds_read_b128 v[194:197], v147 offset:16384
	ds_read_b128 v[198:201], v147 offset:17408
	ds_read_b128 v[202:205], v147 offset:18432
	ds_read_b128 v[206:209], v147 offset:19456
	ds_read_b128 v[228:231], v147 offset:20480
	ds_read_b128 v[232:235], v147 offset:21504
	ds_read_b128 v[236:239], v147 offset:22528
	ds_read_b128 v[240:243], v147 offset:23552
	global_load_lds_dwordx4 v[172:173], off
	s_add_i32 m0, s49, 0x2000
	s_add_u32 s50, s22, 0x100000
	v_lshl_add_u64 v[178:179], s[22:23], 0, v[130:131]
	s_addc_u32 s51, s23, 0
	s_add_i32 s49, s52, s26
	global_load_lds_dwordx4 v[178:179], off
	v_lshl_add_u64 v[180:181], s[50:51], 0, v[0:1]
	s_mov_b32 m0, s49
	v_lshl_add_u64 v[210:211], s[24:25], 0, v[132:133]
	global_load_lds_dwordx4 v[180:181], off
	v_lshl_add_u64 v[180:181], s[50:51], 0, v[130:131]
	s_add_i32 m0, s49, 0x2000
	s_nop 0
	global_load_lds_dwordx4 v[180:181], off
	v_lshl_add_u64 v[180:181], s[24:25], 0, v[134:135]
	s_mov_b32 m0, s31
	s_nop 0
	global_load_lds_dwordx4 v[180:181], off
	s_mov_b32 m0, s36
	s_nop 0
	global_load_lds_dwordx4 v[210:211], off
	s_waitcnt vmcnt(8)
	s_waitcnt lgkmcnt(0)
	s_barrier
	s_setprio 1
	s_waitcnt lgkmcnt(0)
	v_mfma_f32_16x16x32_bf16 v[62:65], v[140:143], v[194:197], v[62:65]
	v_mfma_f32_16x16x32_bf16 v[62:65], v[148:151], v[198:201], v[62:65]
	v_mfma_f32_16x16x32_bf16 v[58:61], v[156:159], v[198:201], v[58:61]
	v_mfma_f32_16x16x32_bf16 v[58:61], v[152:155], v[194:197], v[58:61]
	v_mfma_f32_16x16x32_bf16 v[46:49], v[152:155], v[202:205], v[46:49]
	v_mfma_f32_16x16x32_bf16 v[46:49], v[156:159], v[206:209], v[46:49]
	v_mfma_f32_16x16x32_bf16 v[54:57], v[148:151], v[206:209], v[54:57]
	v_mfma_f32_16x16x32_bf16 v[54:57], v[140:143], v[202:205], v[54:57]
	v_mfma_f32_16x16x32_bf16 v[38:41], v[140:143], v[228:231], v[38:41]
	v_mfma_f32_16x16x32_bf16 v[38:41], v[148:151], v[232:235], v[38:41]
	v_mfma_f32_16x16x32_bf16 v[30:33], v[156:159], v[232:235], v[30:33]
	v_mfma_f32_16x16x32_bf16 v[30:33], v[152:155], v[228:231], v[30:33]
	v_mfma_f32_16x16x32_bf16 v[14:17], v[152:155], v[236:239], v[14:17]
	v_mfma_f32_16x16x32_bf16 v[14:17], v[156:159], v[240:243], v[14:17]
	v_mfma_f32_16x16x32_bf16 v[22:25], v[148:151], v[240:243], v[22:25]
	v_mfma_f32_16x16x32_bf16 v[22:25], v[140:143], v[236:239], v[22:25]
	s_setprio 0
	s_setprio 1
	v_mfma_f32_16x16x32_bf16 v[50:53], v[160:163], v[194:197], v[50:53]
	v_mfma_f32_16x16x32_bf16 v[50:53], v[164:167], v[198:201], v[50:53]
	v_mfma_f32_16x16x32_bf16 v[42:45], v[190:193], v[198:201], v[42:45]
	v_mfma_f32_16x16x32_bf16 v[42:45], v[168:171], v[194:197], v[42:45]
	v_mfma_f32_16x16x32_bf16 v[26:29], v[168:171], v[202:205], v[26:29]
	v_mfma_f32_16x16x32_bf16 v[26:29], v[190:193], v[206:209], v[26:29]
	v_mfma_f32_16x16x32_bf16 v[34:37], v[164:167], v[206:209], v[34:37]
	v_mfma_f32_16x16x32_bf16 v[34:37], v[160:163], v[202:205], v[34:37]
	v_mfma_f32_16x16x32_bf16 v[18:21], v[160:163], v[228:231], v[18:21]
	v_mfma_f32_16x16x32_bf16 v[18:21], v[164:167], v[232:235], v[18:21]
	v_mfma_f32_16x16x32_bf16 v[10:13], v[190:193], v[232:235], v[10:13]
	v_mfma_f32_16x16x32_bf16 v[10:13], v[168:171], v[228:231], v[10:13]
	v_mfma_f32_16x16x32_bf16 v[2:5], v[168:171], v[236:239], v[2:5]
	v_mfma_f32_16x16x32_bf16 v[2:5], v[190:193], v[240:243], v[2:5]
	v_mfma_f32_16x16x32_bf16 v[6:9], v[164:167], v[240:243], v[6:9]
	v_mfma_f32_16x16x32_bf16 v[6:9], v[160:163], v[236:239], v[6:9]
	s_setprio 0
	s_barrier
	s_add_i32 s49, 0, 0x18000
	s_add_i32 s50, 0, 0x1c000
	v_add_u32_e32 v156, s49, v145
	v_add_u32_e32 v175, s50, v145
	ds_read_b128 v[140:143], v156
	ds_read_b128 v[148:151], v156 offset:1024
	ds_read_b128 v[152:155], v156 offset:2048
	ds_read_b128 v[156:159], v156 offset:3072
	ds_read_b128 v[160:163], v175
	ds_read_b128 v[164:167], v175 offset:1024
	ds_read_b128 v[168:171], v175 offset:2048
	ds_read_b128 v[190:193], v175 offset:3072
	s_add_u32 s24, s24, 0x100000
	s_addc_u32 s25, s25, 0
	s_mov_b32 m0, s37
	v_lshl_add_u64 v[244:245], s[24:25], 0, v[134:135]
	ds_read_b128 v[194:197], v147 offset:32768
	ds_read_b128 v[198:201], v147 offset:33792
	ds_read_b128 v[202:205], v147 offset:34816
	ds_read_b128 v[206:209], v147 offset:35840
	ds_read_b128 v[228:231], v147 offset:36864
	ds_read_b128 v[232:235], v147 offset:37888
	ds_read_b128 v[236:239], v147 offset:38912
	ds_read_b128 v[240:243], v147 offset:39936
	global_load_lds_dwordx4 v[244:245], off
	v_lshl_add_u64 v[244:245], s[24:25], 0, v[132:133]
	s_mov_b32 m0, s38
	s_nop 0
	global_load_lds_dwordx4 v[244:245], off
	s_waitcnt vmcnt(8)
	s_waitcnt lgkmcnt(0)
	s_barrier
	s_setprio 1
	s_waitcnt lgkmcnt(0)
	v_mfma_f32_16x16x32_bf16 v[126:129], v[140:143], v[194:197], v[126:129]
	v_mfma_f32_16x16x32_bf16 v[126:129], v[148:151], v[198:201], v[126:129]
	v_mfma_f32_16x16x32_bf16 v[122:125], v[156:159], v[198:201], v[122:125]
	v_mfma_f32_16x16x32_bf16 v[122:125], v[152:155], v[194:197], v[122:125]
	v_mfma_f32_16x16x32_bf16 v[110:113], v[152:155], v[202:205], v[110:113]
	v_mfma_f32_16x16x32_bf16 v[110:113], v[156:159], v[206:209], v[110:113]
	v_mfma_f32_16x16x32_bf16 v[118:121], v[148:151], v[206:209], v[118:121]
	v_mfma_f32_16x16x32_bf16 v[118:121], v[140:143], v[202:205], v[118:121]
	v_mfma_f32_16x16x32_bf16 v[102:105], v[140:143], v[228:231], v[102:105]
	v_mfma_f32_16x16x32_bf16 v[102:105], v[148:151], v[232:235], v[102:105]
	v_mfma_f32_16x16x32_bf16 v[94:97], v[156:159], v[232:235], v[94:97]
	v_mfma_f32_16x16x32_bf16 v[94:97], v[152:155], v[228:231], v[94:97]
	v_mfma_f32_16x16x32_bf16 v[78:81], v[152:155], v[236:239], v[78:81]
	v_mfma_f32_16x16x32_bf16 v[78:81], v[156:159], v[240:243], v[78:81]
	v_mfma_f32_16x16x32_bf16 v[86:89], v[148:151], v[240:243], v[86:89]
	v_mfma_f32_16x16x32_bf16 v[86:89], v[140:143], v[236:239], v[86:89]
	s_setprio 0
	s_setprio 1
	v_mfma_f32_16x16x32_bf16 v[114:117], v[160:163], v[194:197], v[114:117]
	v_mfma_f32_16x16x32_bf16 v[114:117], v[164:167], v[198:201], v[114:117]
	v_mfma_f32_16x16x32_bf16 v[106:109], v[190:193], v[198:201], v[106:109]
	v_mfma_f32_16x16x32_bf16 v[106:109], v[168:171], v[194:197], v[106:109]
	v_mfma_f32_16x16x32_bf16 v[90:93], v[168:171], v[202:205], v[90:93]
	v_mfma_f32_16x16x32_bf16 v[90:93], v[190:193], v[206:209], v[90:93]
	v_mfma_f32_16x16x32_bf16 v[98:101], v[164:167], v[206:209], v[98:101]
	v_mfma_f32_16x16x32_bf16 v[98:101], v[160:163], v[202:205], v[98:101]
	v_mfma_f32_16x16x32_bf16 v[82:85], v[160:163], v[228:231], v[82:85]
	v_mfma_f32_16x16x32_bf16 v[82:85], v[164:167], v[232:235], v[82:85]
	v_mfma_f32_16x16x32_bf16 v[74:77], v[190:193], v[232:235], v[74:77]
	v_mfma_f32_16x16x32_bf16 v[74:77], v[168:171], v[228:231], v[74:77]
	v_mfma_f32_16x16x32_bf16 v[66:69], v[168:171], v[236:239], v[66:69]
	v_mfma_f32_16x16x32_bf16 v[66:69], v[190:193], v[240:243], v[66:69]
	v_mfma_f32_16x16x32_bf16 v[70:73], v[164:167], v[240:243], v[70:73]
	v_mfma_f32_16x16x32_bf16 v[70:73], v[160:163], v[236:239], v[70:73]
	s_setprio 0
	s_barrier
	s_add_i32 s24, s49, s26
	v_lshl_add_u64 v[172:173], v[172:173], 0, s[34:35]
	s_mov_b32 m0, s24
	ds_read_b128 v[194:197], v147 offset:49152
	ds_read_b128 v[198:201], v147 offset:50176
	ds_read_b128 v[202:205], v147 offset:51200
	ds_read_b128 v[206:209], v147 offset:52224
	ds_read_b128 v[228:231], v147 offset:53248
	ds_read_b128 v[232:235], v147 offset:54272
	ds_read_b128 v[236:239], v147 offset:55296
	ds_read_b128 v[240:243], v147 offset:56320
	global_load_lds_dwordx4 v[172:173], off
	s_add_i32 m0, s24, 0x2000
	s_add_u32 s22, s22, 0x100080
	v_lshl_add_u64 v[172:173], v[178:179], 0, s[34:35]
	s_addc_u32 s23, s23, 0
	s_add_i32 s24, s50, s26
	global_load_lds_dwordx4 v[172:173], off
	v_lshl_add_u64 v[172:173], s[22:23], 0, v[0:1]
	s_mov_b32 m0, s24
	s_nop 0
	global_load_lds_dwordx4 v[172:173], off
	v_lshl_add_u64 v[172:173], s[22:23], 0, v[130:131]
	s_add_i32 m0, s24, 0x2000
	s_nop 0
	global_load_lds_dwordx4 v[172:173], off
	v_lshl_add_u64 v[172:173], v[180:181], 0, s[34:35]
	s_mov_b32 m0, s39
	s_nop 0
	global_load_lds_dwordx4 v[172:173], off
	v_lshl_add_u64 v[172:173], v[210:211], 0, s[34:35]
	s_mov_b32 m0, s40
	s_nop 0
	global_load_lds_dwordx4 v[172:173], off
	s_waitcnt vmcnt(8)
	s_waitcnt lgkmcnt(0)
	s_barrier
	s_setprio 1
	s_waitcnt lgkmcnt(0)
	v_mfma_f32_16x16x32_bf16 v[62:65], v[140:143], v[194:197], v[62:65]
	v_mfma_f32_16x16x32_bf16 v[62:65], v[148:151], v[198:201], v[62:65]
	v_mfma_f32_16x16x32_bf16 v[58:61], v[156:159], v[198:201], v[58:61]
	v_mfma_f32_16x16x32_bf16 v[58:61], v[152:155], v[194:197], v[58:61]
	v_mfma_f32_16x16x32_bf16 v[46:49], v[152:155], v[202:205], v[46:49]
	v_mfma_f32_16x16x32_bf16 v[46:49], v[156:159], v[206:209], v[46:49]
	v_mfma_f32_16x16x32_bf16 v[54:57], v[148:151], v[206:209], v[54:57]
	v_mfma_f32_16x16x32_bf16 v[54:57], v[140:143], v[202:205], v[54:57]
	v_mfma_f32_16x16x32_bf16 v[38:41], v[140:143], v[228:231], v[38:41]
	v_mfma_f32_16x16x32_bf16 v[38:41], v[148:151], v[232:235], v[38:41]
	v_mfma_f32_16x16x32_bf16 v[30:33], v[156:159], v[232:235], v[30:33]
	v_mfma_f32_16x16x32_bf16 v[30:33], v[152:155], v[228:231], v[30:33]
	v_mfma_f32_16x16x32_bf16 v[14:17], v[152:155], v[236:239], v[14:17]
	v_mfma_f32_16x16x32_bf16 v[14:17], v[156:159], v[240:243], v[14:17]
	v_mfma_f32_16x16x32_bf16 v[22:25], v[148:151], v[240:243], v[22:25]
	v_mfma_f32_16x16x32_bf16 v[22:25], v[140:143], v[236:239], v[22:25]
	s_setprio 0
	s_setprio 1
	v_mfma_f32_16x16x32_bf16 v[50:53], v[160:163], v[194:197], v[50:53]
	v_mfma_f32_16x16x32_bf16 v[50:53], v[164:167], v[198:201], v[50:53]
	v_mfma_f32_16x16x32_bf16 v[42:45], v[190:193], v[198:201], v[42:45]
	v_mfma_f32_16x16x32_bf16 v[42:45], v[168:171], v[194:197], v[42:45]
	v_mfma_f32_16x16x32_bf16 v[26:29], v[168:171], v[202:205], v[26:29]
	v_mfma_f32_16x16x32_bf16 v[26:29], v[190:193], v[206:209], v[26:29]
	v_mfma_f32_16x16x32_bf16 v[34:37], v[164:167], v[206:209], v[34:37]
	v_mfma_f32_16x16x32_bf16 v[34:37], v[160:163], v[202:205], v[34:37]
	v_mfma_f32_16x16x32_bf16 v[18:21], v[160:163], v[228:231], v[18:21]
	v_mfma_f32_16x16x32_bf16 v[18:21], v[164:167], v[232:235], v[18:21]
	v_mfma_f32_16x16x32_bf16 v[10:13], v[190:193], v[232:235], v[10:13]
	v_mfma_f32_16x16x32_bf16 v[10:13], v[168:171], v[228:231], v[10:13]
	v_mfma_f32_16x16x32_bf16 v[2:5], v[168:171], v[236:239], v[2:5]
	v_mfma_f32_16x16x32_bf16 v[2:5], v[190:193], v[240:243], v[2:5]
	v_mfma_f32_16x16x32_bf16 v[6:9], v[164:167], v[240:243], v[6:9]
	v_mfma_f32_16x16x32_bf16 v[6:9], v[160:163], v[236:239], v[6:9]
	s_setprio 0
	s_barrier
	s_add_i32 s48, s48, 2
	s_add_u32 s18, s18, 0x100
	s_addc_u32 s19, s19, 0
	s_add_u32 s46, s46, 0x100
	s_addc_u32 s47, s47, 0
	s_cmp_gt_u32 s48, 61
	s_cbranch_scc0 .LBB0_139
	s_and_b64 vcc, exec, s[4:5]
	s_cbranch_vccz .LBB0_142
	s_barrier

.LBB0_575:
	s_add_u32 s22, s18, 0xfff00080
	s_addc_u32 s23, s19, -1
	s_add_i32 s53, 0, 0x10000
	s_cmp_eq_u32 s52, 60
	s_cselect_b32 s25, s9, s23
	s_cselect_b32 s24, s48, s22
	v_add_u32_e32 v140, s53, v143
	s_cselect_b32 s23, s7, s51
	s_cselect_b32 s22, s49, s50
	s_add_i32 s56, 0, 0x14000
	ds_read_b128 v[146:149], v140
	ds_read_b128 v[150:153], v140 offset:1024
	ds_read_b128 v[154:157], v140 offset:2048
	ds_read_b128 v[158:161], v140 offset:3072
	v_add_u32_e32 v140, s56, v143
	ds_read_b128 v[162:165], v140
	ds_read_b128 v[166:169], v140 offset:1024
	ds_read_b128 v[170:173], v140 offset:2048
	ds_read_b128 v[178:181], v140 offset:3072
	v_lshl_add_u64 v[140:141], s[18:19], 0, v[136:137]
	s_add_i32 m0, s39, 0xc000
	ds_read_b128 v[190:193], v145
	ds_read_b128 v[194:197], v145 offset:1024
	ds_read_b128 v[198:201], v145 offset:2048
	ds_read_b128 v[202:205], v145 offset:3072
	ds_read_b128 v[206:209], v145 offset:4096
	ds_read_b128 v[228:231], v145 offset:5120
	ds_read_b128 v[232:235], v145 offset:6144
	ds_read_b128 v[236:239], v145 offset:7168
	global_load_lds_dwordx4 v[140:141], off
	v_lshl_add_u64 v[140:141], s[18:19], 0, v[138:139]
	s_add_i32 m0, s39, 0xe000
	s_nop 0
	global_load_lds_dwordx4 v[140:141], off
	s_waitcnt vmcnt(8)
	s_waitcnt lgkmcnt(0)
	s_barrier
	s_setprio 1
	s_waitcnt lgkmcnt(0)
	v_mfma_f32_16x16x32_bf16 v[126:129], v[146:149], v[190:193], v[126:129]
	v_mfma_f32_16x16x32_bf16 v[126:129], v[150:153], v[194:197], v[126:129]
	v_mfma_f32_16x16x32_bf16 v[122:125], v[158:161], v[194:197], v[122:125]
	v_mfma_f32_16x16x32_bf16 v[122:125], v[154:157], v[190:193], v[122:125]
	v_mfma_f32_16x16x32_bf16 v[110:113], v[154:157], v[198:201], v[110:113]
	v_mfma_f32_16x16x32_bf16 v[110:113], v[158:161], v[202:205], v[110:113]
	v_mfma_f32_16x16x32_bf16 v[118:121], v[150:153], v[202:205], v[118:121]
	v_mfma_f32_16x16x32_bf16 v[118:121], v[146:149], v[198:201], v[118:121]
	v_mfma_f32_16x16x32_bf16 v[102:105], v[146:149], v[206:209], v[102:105]
	v_mfma_f32_16x16x32_bf16 v[102:105], v[150:153], v[228:231], v[102:105]
	v_mfma_f32_16x16x32_bf16 v[94:97], v[158:161], v[228:231], v[94:97]
	v_mfma_f32_16x16x32_bf16 v[94:97], v[154:157], v[206:209], v[94:97]
	v_mfma_f32_16x16x32_bf16 v[78:81], v[154:157], v[232:235], v[78:81]
	v_mfma_f32_16x16x32_bf16 v[78:81], v[158:161], v[236:239], v[78:81]
	v_mfma_f32_16x16x32_bf16 v[86:89], v[150:153], v[236:239], v[86:89]
	v_mfma_f32_16x16x32_bf16 v[86:89], v[146:149], v[232:235], v[86:89]
	s_setprio 0
	s_setprio 1
	v_mfma_f32_16x16x32_bf16 v[114:117], v[162:165], v[190:193], v[114:117]
	v_mfma_f32_16x16x32_bf16 v[114:117], v[166:169], v[194:197], v[114:117]
	v_mfma_f32_16x16x32_bf16 v[106:109], v[178:181], v[194:197], v[106:109]
	v_mfma_f32_16x16x32_bf16 v[106:109], v[170:173], v[190:193], v[106:109]
	v_mfma_f32_16x16x32_bf16 v[90:93], v[170:173], v[198:201], v[90:93]
	v_mfma_f32_16x16x32_bf16 v[90:93], v[178:181], v[202:205], v[90:93]
	v_mfma_f32_16x16x32_bf16 v[98:101], v[166:169], v[202:205], v[98:101]
	v_mfma_f32_16x16x32_bf16 v[98:101], v[162:165], v[198:201], v[98:101]
	v_mfma_f32_16x16x32_bf16 v[82:85], v[162:165], v[206:209], v[82:85]
	v_mfma_f32_16x16x32_bf16 v[82:85], v[166:169], v[228:231], v[82:85]
	v_mfma_f32_16x16x32_bf16 v[74:77], v[178:181], v[228:231], v[74:77]
	v_mfma_f32_16x16x32_bf16 v[74:77], v[170:173], v[206:209], v[74:77]
	v_mfma_f32_16x16x32_bf16 v[66:69], v[170:173], v[232:235], v[66:69]
	v_mfma_f32_16x16x32_bf16 v[66:69], v[178:181], v[236:239], v[66:69]
	v_mfma_f32_16x16x32_bf16 v[70:73], v[166:169], v[236:239], v[70:73]
	v_mfma_f32_16x16x32_bf16 v[70:73], v[162:165], v[232:235], v[70:73]
	s_setprio 0
	s_barrier
	s_add_i32 s53, s53, s38
	v_lshl_add_u64 v[140:141], s[22:23], 0, v[0:1]
	s_mov_b32 m0, s53
	ds_read_b128 v[190:193], v145 offset:16384
	ds_read_b128 v[194:197], v145 offset:17408
	ds_read_b128 v[198:201], v145 offset:18432
	ds_read_b128 v[202:205], v145 offset:19456
	ds_read_b128 v[206:209], v145 offset:20480
	ds_read_b128 v[228:231], v145 offset:21504
	ds_read_b128 v[232:235], v145 offset:22528
	ds_read_b128 v[236:239], v145 offset:23552
	global_load_lds_dwordx4 v[140:141], off
	s_add_i32 m0, s53, 0x2000
	s_add_u32 s54, s22, 0x100000
	v_lshl_add_u64 v[186:187], s[22:23], 0, v[130:131]
	s_addc_u32 s55, s23, 0
	s_add_i32 s53, s56, s38
	global_load_lds_dwordx4 v[186:187], off
	v_lshl_add_u64 v[188:189], s[54:55], 0, v[0:1]
	s_mov_b32 m0, s53
	v_lshl_add_u64 v[210:211], s[24:25], 0, v[132:133]
	global_load_lds_dwordx4 v[188:189], off
	v_lshl_add_u64 v[188:189], s[54:55], 0, v[130:131]
	s_add_i32 m0, s53, 0x2000
	s_nop 0
	global_load_lds_dwordx4 v[188:189], off
	v_lshl_add_u64 v[188:189], s[24:25], 0, v[134:135]
	s_mov_b32 m0, s39
	s_nop 0
	global_load_lds_dwordx4 v[188:189], off
	s_mov_b32 m0, s40
	s_nop 0
	global_load_lds_dwordx4 v[210:211], off
	s_waitcnt vmcnt(8)
	s_waitcnt lgkmcnt(0)
	s_barrier
	s_setprio 1
	s_waitcnt lgkmcnt(0)
	v_mfma_f32_16x16x32_bf16 v[62:65], v[146:149], v[190:193], v[62:65]
	v_mfma_f32_16x16x32_bf16 v[62:65], v[150:153], v[194:197], v[62:65]
	v_mfma_f32_16x16x32_bf16 v[58:61], v[158:161], v[194:197], v[58:61]
	v_mfma_f32_16x16x32_bf16 v[58:61], v[154:157], v[190:193], v[58:61]
	v_mfma_f32_16x16x32_bf16 v[46:49], v[154:157], v[198:201], v[46:49]
	v_mfma_f32_16x16x32_bf16 v[46:49], v[158:161], v[202:205], v[46:49]
	v_mfma_f32_16x16x32_bf16 v[54:57], v[150:153], v[202:205], v[54:57]
	v_mfma_f32_16x16x32_bf16 v[54:57], v[146:149], v[198:201], v[54:57]
	v_mfma_f32_16x16x32_bf16 v[38:41], v[146:149], v[206:209], v[38:41]
	v_mfma_f32_16x16x32_bf16 v[38:41], v[150:153], v[228:231], v[38:41]
	v_mfma_f32_16x16x32_bf16 v[30:33], v[158:161], v[228:231], v[30:33]
	v_mfma_f32_16x16x32_bf16 v[30:33], v[154:157], v[206:209], v[30:33]
	v_mfma_f32_16x16x32_bf16 v[14:17], v[154:157], v[232:235], v[14:17]
	v_mfma_f32_16x16x32_bf16 v[14:17], v[158:161], v[236:239], v[14:17]
	v_mfma_f32_16x16x32_bf16 v[22:25], v[150:153], v[236:239], v[22:25]
	v_mfma_f32_16x16x32_bf16 v[22:25], v[146:149], v[232:235], v[22:25]
	s_setprio 0
	s_setprio 1
	v_mfma_f32_16x16x32_bf16 v[50:53], v[162:165], v[190:193], v[50:53]
	v_mfma_f32_16x16x32_bf16 v[50:53], v[166:169], v[194:197], v[50:53]
	v_mfma_f32_16x16x32_bf16 v[42:45], v[178:181], v[194:197], v[42:45]
	v_mfma_f32_16x16x32_bf16 v[42:45], v[170:173], v[190:193], v[42:45]
	v_mfma_f32_16x16x32_bf16 v[26:29], v[170:173], v[198:201], v[26:29]
	v_mfma_f32_16x16x32_bf16 v[26:29], v[178:181], v[202:205], v[26:29]
	v_mfma_f32_16x16x32_bf16 v[34:37], v[166:169], v[202:205], v[34:37]
	v_mfma_f32_16x16x32_bf16 v[34:37], v[162:165], v[198:201], v[34:37]
	v_mfma_f32_16x16x32_bf16 v[18:21], v[162:165], v[206:209], v[18:21]
	v_mfma_f32_16x16x32_bf16 v[18:21], v[166:169], v[228:231], v[18:21]
	v_mfma_f32_16x16x32_bf16 v[10:13], v[178:181], v[228:231], v[10:13]
	v_mfma_f32_16x16x32_bf16 v[10:13], v[170:173], v[206:209], v[10:13]
	v_mfma_f32_16x16x32_bf16 v[2:5], v[170:173], v[232:235], v[2:5]
	v_mfma_f32_16x16x32_bf16 v[2:5], v[178:181], v[236:239], v[2:5]
	v_mfma_f32_16x16x32_bf16 v[6:9], v[166:169], v[236:239], v[6:9]
	v_mfma_f32_16x16x32_bf16 v[6:9], v[162:165], v[232:235], v[6:9]
	s_setprio 0
	s_barrier
	s_add_i32 s53, 0, 0x18000
	s_add_i32 s54, 0, 0x1c000
	v_add_u32_e32 v158, s53, v143
	v_add_u32_e32 v175, s54, v143
	ds_read_b128 v[146:149], v158
	ds_read_b128 v[150:153], v158 offset:1024
	ds_read_b128 v[154:157], v158 offset:2048
	ds_read_b128 v[158:161], v158 offset:3072
	ds_read_b128 v[162:165], v175
	ds_read_b128 v[166:169], v175 offset:1024
	ds_read_b128 v[170:173], v175 offset:2048
	ds_read_b128 v[178:181], v175 offset:3072
	s_add_u32 s24, s24, 0x100000
	s_addc_u32 s25, s25, 0
	s_mov_b32 m0, s41
	v_lshl_add_u64 v[226:227], s[24:25], 0, v[134:135]
	ds_read_b128 v[190:193], v145 offset:32768
	ds_read_b128 v[194:197], v145 offset:33792
	ds_read_b128 v[198:201], v145 offset:34816
	ds_read_b128 v[202:205], v145 offset:35840
	ds_read_b128 v[206:209], v145 offset:36864
	ds_read_b128 v[228:231], v145 offset:37888
	ds_read_b128 v[232:235], v145 offset:38912
	ds_read_b128 v[236:239], v145 offset:39936
	global_load_lds_dwordx4 v[226:227], off
	v_lshl_add_u64 v[226:227], s[24:25], 0, v[132:133]
	s_mov_b32 m0, s42
	s_nop 0
	global_load_lds_dwordx4 v[226:227], off
	s_waitcnt vmcnt(8)
	s_waitcnt lgkmcnt(0)
	s_barrier
	s_setprio 1
	s_waitcnt lgkmcnt(0)
	v_mfma_f32_16x16x32_bf16 v[126:129], v[146:149], v[190:193], v[126:129]
	v_mfma_f32_16x16x32_bf16 v[126:129], v[150:153], v[194:197], v[126:129]
	v_mfma_f32_16x16x32_bf16 v[122:125], v[158:161], v[194:197], v[122:125]
	v_mfma_f32_16x16x32_bf16 v[122:125], v[154:157], v[190:193], v[122:125]
	v_mfma_f32_16x16x32_bf16 v[110:113], v[154:157], v[198:201], v[110:113]
	v_mfma_f32_16x16x32_bf16 v[110:113], v[158:161], v[202:205], v[110:113]
	v_mfma_f32_16x16x32_bf16 v[118:121], v[150:153], v[202:205], v[118:121]
	v_mfma_f32_16x16x32_bf16 v[118:121], v[146:149], v[198:201], v[118:121]
	v_mfma_f32_16x16x32_bf16 v[102:105], v[146:149], v[206:209], v[102:105]
	v_mfma_f32_16x16x32_bf16 v[102:105], v[150:153], v[228:231], v[102:105]
	v_mfma_f32_16x16x32_bf16 v[94:97], v[158:161], v[228:231], v[94:97]
	v_mfma_f32_16x16x32_bf16 v[94:97], v[154:157], v[206:209], v[94:97]
	v_mfma_f32_16x16x32_bf16 v[78:81], v[154:157], v[232:235], v[78:81]
	v_mfma_f32_16x16x32_bf16 v[78:81], v[158:161], v[236:239], v[78:81]
	v_mfma_f32_16x16x32_bf16 v[86:89], v[150:153], v[236:239], v[86:89]
	v_mfma_f32_16x16x32_bf16 v[86:89], v[146:149], v[232:235], v[86:89]
	s_setprio 0
	s_setprio 1
	v_mfma_f32_16x16x32_bf16 v[114:117], v[162:165], v[190:193], v[114:117]
	v_mfma_f32_16x16x32_bf16 v[114:117], v[166:169], v[194:197], v[114:117]
	v_mfma_f32_16x16x32_bf16 v[106:109], v[178:181], v[194:197], v[106:109]
	v_mfma_f32_16x16x32_bf16 v[106:109], v[170:173], v[190:193], v[106:109]
	v_mfma_f32_16x16x32_bf16 v[90:93], v[170:173], v[198:201], v[90:93]
	v_mfma_f32_16x16x32_bf16 v[90:93], v[178:181], v[202:205], v[90:93]
	v_mfma_f32_16x16x32_bf16 v[98:101], v[166:169], v[202:205], v[98:101]
	v_mfma_f32_16x16x32_bf16 v[98:101], v[162:165], v[198:201], v[98:101]
	v_mfma_f32_16x16x32_bf16 v[82:85], v[162:165], v[206:209], v[82:85]
	v_mfma_f32_16x16x32_bf16 v[82:85], v[166:169], v[228:231], v[82:85]
	v_mfma_f32_16x16x32_bf16 v[74:77], v[178:181], v[228:231], v[74:77]
	v_mfma_f32_16x16x32_bf16 v[74:77], v[170:173], v[206:209], v[74:77]
	v_mfma_f32_16x16x32_bf16 v[66:69], v[170:173], v[232:235], v[66:69]
	v_mfma_f32_16x16x32_bf16 v[66:69], v[178:181], v[236:239], v[66:69]
	v_mfma_f32_16x16x32_bf16 v[70:73], v[166:169], v[236:239], v[70:73]
	v_mfma_f32_16x16x32_bf16 v[70:73], v[162:165], v[232:235], v[70:73]
	s_setprio 0
	s_barrier
	s_add_i32 s24, s53, s38
	v_lshl_add_u64 v[140:141], v[140:141], 0, s[34:35]
	s_mov_b32 m0, s24
	ds_read_b128 v[190:193], v145 offset:49152
	ds_read_b128 v[194:197], v145 offset:50176
	ds_read_b128 v[198:201], v145 offset:51200
	ds_read_b128 v[202:205], v145 offset:52224
	ds_read_b128 v[206:209], v145 offset:53248
	ds_read_b128 v[228:231], v145 offset:54272
	ds_read_b128 v[232:235], v145 offset:55296
	ds_read_b128 v[236:239], v145 offset:56320
	global_load_lds_dwordx4 v[140:141], off
	s_add_i32 m0, s24, 0x2000
	s_add_u32 s22, s22, 0x100080
	v_lshl_add_u64 v[140:141], v[186:187], 0, s[34:35]
	s_addc_u32 s23, s23, 0
	s_add_i32 s24, s54, s38
	global_load_lds_dwordx4 v[140:141], off
	v_lshl_add_u64 v[140:141], s[22:23], 0, v[0:1]
	s_mov_b32 m0, s24
	s_nop 0
	global_load_lds_dwordx4 v[140:141], off
	v_lshl_add_u64 v[140:141], s[22:23], 0, v[130:131]
	s_add_i32 m0, s24, 0x2000
	s_nop 0
	global_load_lds_dwordx4 v[140:141], off
	v_lshl_add_u64 v[140:141], v[188:189], 0, s[34:35]
	s_mov_b32 m0, s43
	s_nop 0
	global_load_lds_dwordx4 v[140:141], off
	v_lshl_add_u64 v[140:141], v[210:211], 0, s[34:35]
	s_mov_b32 m0, s44
	s_nop 0
	global_load_lds_dwordx4 v[140:141], off
	s_waitcnt vmcnt(8)
	s_waitcnt lgkmcnt(0)
	s_barrier
	s_setprio 1
	s_waitcnt lgkmcnt(0)
	v_mfma_f32_16x16x32_bf16 v[62:65], v[146:149], v[190:193], v[62:65]
	v_mfma_f32_16x16x32_bf16 v[62:65], v[150:153], v[194:197], v[62:65]
	v_mfma_f32_16x16x32_bf16 v[58:61], v[158:161], v[194:197], v[58:61]
	v_mfma_f32_16x16x32_bf16 v[58:61], v[154:157], v[190:193], v[58:61]
	v_mfma_f32_16x16x32_bf16 v[46:49], v[154:157], v[198:201], v[46:49]
	v_mfma_f32_16x16x32_bf16 v[46:49], v[158:161], v[202:205], v[46:49]
	v_mfma_f32_16x16x32_bf16 v[54:57], v[150:153], v[202:205], v[54:57]
	v_mfma_f32_16x16x32_bf16 v[54:57], v[146:149], v[198:201], v[54:57]
	v_mfma_f32_16x16x32_bf16 v[38:41], v[146:149], v[206:209], v[38:41]
	v_mfma_f32_16x16x32_bf16 v[38:41], v[150:153], v[228:231], v[38:41]
	v_mfma_f32_16x16x32_bf16 v[30:33], v[158:161], v[228:231], v[30:33]
	v_mfma_f32_16x16x32_bf16 v[30:33], v[154:157], v[206:209], v[30:33]
	v_mfma_f32_16x16x32_bf16 v[14:17], v[154:157], v[232:235], v[14:17]
	v_mfma_f32_16x16x32_bf16 v[14:17], v[158:161], v[236:239], v[14:17]
	v_mfma_f32_16x16x32_bf16 v[22:25], v[150:153], v[236:239], v[22:25]
	v_mfma_f32_16x16x32_bf16 v[22:25], v[146:149], v[232:235], v[22:25]
	s_setprio 0
	s_setprio 1
	v_mfma_f32_16x16x32_bf16 v[50:53], v[162:165], v[190:193], v[50:53]
	v_mfma_f32_16x16x32_bf16 v[50:53], v[166:169], v[194:197], v[50:53]
	v_mfma_f32_16x16x32_bf16 v[42:45], v[178:181], v[194:197], v[42:45]
	v_mfma_f32_16x16x32_bf16 v[42:45], v[170:173], v[190:193], v[42:45]
	v_mfma_f32_16x16x32_bf16 v[26:29], v[170:173], v[198:201], v[26:29]
	v_mfma_f32_16x16x32_bf16 v[26:29], v[178:181], v[202:205], v[26:29]
	v_mfma_f32_16x16x32_bf16 v[34:37], v[166:169], v[202:205], v[34:37]
	v_mfma_f32_16x16x32_bf16 v[34:37], v[162:165], v[198:201], v[34:37]
	v_mfma_f32_16x16x32_bf16 v[18:21], v[162:165], v[206:209], v[18:21]
	v_mfma_f32_16x16x32_bf16 v[18:21], v[166:169], v[228:231], v[18:21]
	v_mfma_f32_16x16x32_bf16 v[10:13], v[178:181], v[228:231], v[10:13]
	v_mfma_f32_16x16x32_bf16 v[10:13], v[170:173], v[206:209], v[10:13]
	v_mfma_f32_16x16x32_bf16 v[2:5], v[170:173], v[232:235], v[2:5]
	v_mfma_f32_16x16x32_bf16 v[2:5], v[178:181], v[236:239], v[2:5]
	v_mfma_f32_16x16x32_bf16 v[6:9], v[166:169], v[236:239], v[6:9]
	v_mfma_f32_16x16x32_bf16 v[6:9], v[162:165], v[232:235], v[6:9]
	s_setprio 0
	s_barrier
	s_add_i32 s52, s52, 2
	s_add_u32 s18, s18, 0x100
	s_addc_u32 s19, s19, 0
	s_add_u32 s50, s50, 0x100
	s_addc_u32 s51, s51, 0
	s_cmp_gt_u32 s52, 61
	s_cbranch_scc0 .LBB0_575
	s_and_b64 vcc, exec, s[4:5]
	s_cbranch_vccz .LBB0_578
	s_barrier

.LBB0_721:
	s_add_u32 s18, s16, 0xfff00080
	s_addc_u32 s19, s17, -1
	s_add_i32 s53, 0, 0x10000
	s_cmp_eq_u32 s52, 60
	s_cselect_b32 s23, s7, s19
	s_cselect_b32 s22, s48, s18
	v_add_u32_e32 v140, s53, v143
	s_cselect_b32 s19, s5, s51
	s_cselect_b32 s18, s49, s50
	s_add_i32 s56, 0, 0x14000
	ds_read_b128 v[146:149], v140
	ds_read_b128 v[150:153], v140 offset:1024
	ds_read_b128 v[154:157], v140 offset:2048
	ds_read_b128 v[158:161], v140 offset:3072
	v_add_u32_e32 v140, s56, v143
	ds_read_b128 v[162:165], v140
	ds_read_b128 v[166:169], v140 offset:1024
	ds_read_b128 v[170:173], v140 offset:2048
	ds_read_b128 v[178:181], v140 offset:3072
	v_lshl_add_u64 v[140:141], s[16:17], 0, v[136:137]
	s_add_i32 m0, s31, 0xc000
	ds_read_b128 v[190:193], v145
	ds_read_b128 v[194:197], v145 offset:1024
	ds_read_b128 v[198:201], v145 offset:2048
	ds_read_b128 v[202:205], v145 offset:3072
	ds_read_b128 v[206:209], v145 offset:4096
	ds_read_b128 v[228:231], v145 offset:5120
	ds_read_b128 v[232:235], v145 offset:6144
	ds_read_b128 v[236:239], v145 offset:7168
	global_load_lds_dwordx4 v[140:141], off
	v_lshl_add_u64 v[140:141], s[16:17], 0, v[138:139]
	s_add_i32 m0, s31, 0xe000
	s_nop 0
	global_load_lds_dwordx4 v[140:141], off
	s_waitcnt vmcnt(8)
	s_waitcnt lgkmcnt(0)
	s_barrier
	s_setprio 1
	s_waitcnt lgkmcnt(0)
	v_mfma_f32_16x16x32_bf16 v[126:129], v[146:149], v[190:193], v[126:129]
	v_mfma_f32_16x16x32_bf16 v[126:129], v[150:153], v[194:197], v[126:129]
	v_mfma_f32_16x16x32_bf16 v[118:121], v[158:161], v[194:197], v[118:121]
	v_mfma_f32_16x16x32_bf16 v[118:121], v[154:157], v[190:193], v[118:121]
	v_mfma_f32_16x16x32_bf16 v[102:105], v[154:157], v[198:201], v[102:105]
	v_mfma_f32_16x16x32_bf16 v[102:105], v[158:161], v[202:205], v[102:105]
	v_mfma_f32_16x16x32_bf16 v[110:113], v[150:153], v[202:205], v[110:113]
	v_mfma_f32_16x16x32_bf16 v[110:113], v[146:149], v[198:201], v[110:113]
	v_mfma_f32_16x16x32_bf16 v[94:97], v[146:149], v[206:209], v[94:97]
	v_mfma_f32_16x16x32_bf16 v[94:97], v[150:153], v[228:231], v[94:97]
	v_mfma_f32_16x16x32_bf16 v[86:89], v[158:161], v[228:231], v[86:89]
	v_mfma_f32_16x16x32_bf16 v[86:89], v[154:157], v[206:209], v[86:89]
	v_mfma_f32_16x16x32_bf16 v[70:73], v[154:157], v[232:235], v[70:73]
	v_mfma_f32_16x16x32_bf16 v[70:73], v[158:161], v[236:239], v[70:73]
	v_mfma_f32_16x16x32_bf16 v[78:81], v[150:153], v[236:239], v[78:81]
	v_mfma_f32_16x16x32_bf16 v[78:81], v[146:149], v[232:235], v[78:81]
	s_setprio 0
	s_setprio 1
	v_mfma_f32_16x16x32_bf16 v[122:125], v[162:165], v[190:193], v[122:125]
	v_mfma_f32_16x16x32_bf16 v[122:125], v[166:169], v[194:197], v[122:125]
	v_mfma_f32_16x16x32_bf16 v[114:117], v[178:181], v[194:197], v[114:117]
	v_mfma_f32_16x16x32_bf16 v[114:117], v[170:173], v[190:193], v[114:117]
	v_mfma_f32_16x16x32_bf16 v[98:101], v[170:173], v[198:201], v[98:101]
	v_mfma_f32_16x16x32_bf16 v[98:101], v[178:181], v[202:205], v[98:101]
	v_mfma_f32_16x16x32_bf16 v[106:109], v[166:169], v[202:205], v[106:109]
	v_mfma_f32_16x16x32_bf16 v[106:109], v[162:165], v[198:201], v[106:109]
	v_mfma_f32_16x16x32_bf16 v[90:93], v[162:165], v[206:209], v[90:93]
	v_mfma_f32_16x16x32_bf16 v[90:93], v[166:169], v[228:231], v[90:93]
	v_mfma_f32_16x16x32_bf16 v[82:85], v[178:181], v[228:231], v[82:85]
	v_mfma_f32_16x16x32_bf16 v[82:85], v[170:173], v[206:209], v[82:85]
	v_mfma_f32_16x16x32_bf16 v[66:69], v[170:173], v[232:235], v[66:69]
	v_mfma_f32_16x16x32_bf16 v[66:69], v[178:181], v[236:239], v[66:69]
	v_mfma_f32_16x16x32_bf16 v[74:77], v[166:169], v[236:239], v[74:77]
	v_mfma_f32_16x16x32_bf16 v[74:77], v[162:165], v[232:235], v[74:77]
	s_setprio 0
	s_barrier
	s_add_i32 s53, s53, s26
	v_lshl_add_u64 v[140:141], s[18:19], 0, v[0:1]
	s_mov_b32 m0, s53
	ds_read_b128 v[190:193], v145 offset:16384
	ds_read_b128 v[194:197], v145 offset:17408
	ds_read_b128 v[198:201], v145 offset:18432
	ds_read_b128 v[202:205], v145 offset:19456
	ds_read_b128 v[206:209], v145 offset:20480
	ds_read_b128 v[228:231], v145 offset:21504
	ds_read_b128 v[232:235], v145 offset:22528
	ds_read_b128 v[236:239], v145 offset:23552
	global_load_lds_dwordx4 v[140:141], off
	s_add_i32 m0, s53, 0x2000
	s_add_u32 s54, s18, 0x100000
	v_lshl_add_u64 v[186:187], s[18:19], 0, v[130:131]
	s_addc_u32 s55, s19, 0
	s_add_i32 s53, s56, s26
	global_load_lds_dwordx4 v[186:187], off
	v_lshl_add_u64 v[188:189], s[54:55], 0, v[0:1]
	s_mov_b32 m0, s53
	v_lshl_add_u64 v[210:211], s[22:23], 0, v[132:133]
	global_load_lds_dwordx4 v[188:189], off
	v_lshl_add_u64 v[188:189], s[54:55], 0, v[130:131]
	s_add_i32 m0, s53, 0x2000
	s_nop 0
	global_load_lds_dwordx4 v[188:189], off
	v_lshl_add_u64 v[188:189], s[22:23], 0, v[134:135]
	s_mov_b32 m0, s31
	s_nop 0
	global_load_lds_dwordx4 v[188:189], off
	s_mov_b32 m0, s40
	s_nop 0
	global_load_lds_dwordx4 v[210:211], off
	s_waitcnt vmcnt(8)
	s_waitcnt lgkmcnt(0)
	s_barrier
	s_setprio 1
	s_waitcnt lgkmcnt(0)
	v_mfma_f32_16x16x32_bf16 v[62:65], v[146:149], v[190:193], v[62:65]
	v_mfma_f32_16x16x32_bf16 v[62:65], v[150:153], v[194:197], v[62:65]
	v_mfma_f32_16x16x32_bf16 v[54:57], v[158:161], v[194:197], v[54:57]
	v_mfma_f32_16x16x32_bf16 v[54:57], v[154:157], v[190:193], v[54:57]
	v_mfma_f32_16x16x32_bf16 v[38:41], v[154:157], v[198:201], v[38:41]
	v_mfma_f32_16x16x32_bf16 v[38:41], v[158:161], v[202:205], v[38:41]
	v_mfma_f32_16x16x32_bf16 v[46:49], v[150:153], v[202:205], v[46:49]
	v_mfma_f32_16x16x32_bf16 v[46:49], v[146:149], v[198:201], v[46:49]
	v_mfma_f32_16x16x32_bf16 v[30:33], v[146:149], v[206:209], v[30:33]
	v_mfma_f32_16x16x32_bf16 v[30:33], v[150:153], v[228:231], v[30:33]
	v_mfma_f32_16x16x32_bf16 v[22:25], v[158:161], v[228:231], v[22:25]
	v_mfma_f32_16x16x32_bf16 v[22:25], v[154:157], v[206:209], v[22:25]
	v_mfma_f32_16x16x32_bf16 v[6:9], v[154:157], v[232:235], v[6:9]
	v_mfma_f32_16x16x32_bf16 v[6:9], v[158:161], v[236:239], v[6:9]
	v_mfma_f32_16x16x32_bf16 v[14:17], v[150:153], v[236:239], v[14:17]
	v_mfma_f32_16x16x32_bf16 v[14:17], v[146:149], v[232:235], v[14:17]
	s_setprio 0
	s_setprio 1
	v_mfma_f32_16x16x32_bf16 v[58:61], v[162:165], v[190:193], v[58:61]
	v_mfma_f32_16x16x32_bf16 v[58:61], v[166:169], v[194:197], v[58:61]
	v_mfma_f32_16x16x32_bf16 v[50:53], v[178:181], v[194:197], v[50:53]
	v_mfma_f32_16x16x32_bf16 v[50:53], v[170:173], v[190:193], v[50:53]
	v_mfma_f32_16x16x32_bf16 v[34:37], v[170:173], v[198:201], v[34:37]
	v_mfma_f32_16x16x32_bf16 v[34:37], v[178:181], v[202:205], v[34:37]
	v_mfma_f32_16x16x32_bf16 v[42:45], v[166:169], v[202:205], v[42:45]
	v_mfma_f32_16x16x32_bf16 v[42:45], v[162:165], v[198:201], v[42:45]
	v_mfma_f32_16x16x32_bf16 v[26:29], v[162:165], v[206:209], v[26:29]
	v_mfma_f32_16x16x32_bf16 v[26:29], v[166:169], v[228:231], v[26:29]
	v_mfma_f32_16x16x32_bf16 v[18:21], v[178:181], v[228:231], v[18:21]
	v_mfma_f32_16x16x32_bf16 v[18:21], v[170:173], v[206:209], v[18:21]
	v_mfma_f32_16x16x32_bf16 v[2:5], v[170:173], v[232:235], v[2:5]
	v_mfma_f32_16x16x32_bf16 v[2:5], v[178:181], v[236:239], v[2:5]
	v_mfma_f32_16x16x32_bf16 v[10:13], v[166:169], v[236:239], v[10:13]
	v_mfma_f32_16x16x32_bf16 v[10:13], v[162:165], v[232:235], v[10:13]
	s_setprio 0
	s_barrier
	s_add_i32 s53, 0, 0x18000
	s_add_i32 s54, 0, 0x1c000
	v_add_u32_e32 v158, s53, v143
	v_add_u32_e32 v175, s54, v143
	ds_read_b128 v[146:149], v158
	ds_read_b128 v[150:153], v158 offset:1024
	ds_read_b128 v[154:157], v158 offset:2048
	ds_read_b128 v[158:161], v158 offset:3072
	ds_read_b128 v[162:165], v175
	ds_read_b128 v[166:169], v175 offset:1024
	ds_read_b128 v[170:173], v175 offset:2048
	ds_read_b128 v[178:181], v175 offset:3072
	s_add_u32 s22, s22, 0x100000
	s_addc_u32 s23, s23, 0
	s_mov_b32 m0, s41
	v_lshl_add_u64 v[226:227], s[22:23], 0, v[134:135]
	ds_read_b128 v[190:193], v145 offset:32768
	ds_read_b128 v[194:197], v145 offset:33792
	ds_read_b128 v[198:201], v145 offset:34816
	ds_read_b128 v[202:205], v145 offset:35840
	ds_read_b128 v[206:209], v145 offset:36864
	ds_read_b128 v[228:231], v145 offset:37888
	ds_read_b128 v[232:235], v145 offset:38912
	ds_read_b128 v[236:239], v145 offset:39936
	global_load_lds_dwordx4 v[226:227], off
	v_lshl_add_u64 v[226:227], s[22:23], 0, v[132:133]
	s_mov_b32 m0, s42
	s_nop 0
	global_load_lds_dwordx4 v[226:227], off
	s_waitcnt vmcnt(8)
	s_waitcnt lgkmcnt(0)
	s_barrier
	s_setprio 1
	s_waitcnt lgkmcnt(0)
	v_mfma_f32_16x16x32_bf16 v[126:129], v[146:149], v[190:193], v[126:129]
	v_mfma_f32_16x16x32_bf16 v[126:129], v[150:153], v[194:197], v[126:129]
	v_mfma_f32_16x16x32_bf16 v[118:121], v[158:161], v[194:197], v[118:121]
	v_mfma_f32_16x16x32_bf16 v[118:121], v[154:157], v[190:193], v[118:121]
	v_mfma_f32_16x16x32_bf16 v[102:105], v[154:157], v[198:201], v[102:105]
	v_mfma_f32_16x16x32_bf16 v[102:105], v[158:161], v[202:205], v[102:105]
	v_mfma_f32_16x16x32_bf16 v[110:113], v[150:153], v[202:205], v[110:113]
	v_mfma_f32_16x16x32_bf16 v[110:113], v[146:149], v[198:201], v[110:113]
	v_mfma_f32_16x16x32_bf16 v[94:97], v[146:149], v[206:209], v[94:97]
	v_mfma_f32_16x16x32_bf16 v[94:97], v[150:153], v[228:231], v[94:97]
	v_mfma_f32_16x16x32_bf16 v[86:89], v[158:161], v[228:231], v[86:89]
	v_mfma_f32_16x16x32_bf16 v[86:89], v[154:157], v[206:209], v[86:89]
	v_mfma_f32_16x16x32_bf16 v[70:73], v[154:157], v[232:235], v[70:73]
	v_mfma_f32_16x16x32_bf16 v[70:73], v[158:161], v[236:239], v[70:73]
	v_mfma_f32_16x16x32_bf16 v[78:81], v[150:153], v[236:239], v[78:81]
	v_mfma_f32_16x16x32_bf16 v[78:81], v[146:149], v[232:235], v[78:81]
	s_setprio 0
	s_setprio 1
	v_mfma_f32_16x16x32_bf16 v[122:125], v[162:165], v[190:193], v[122:125]
	v_mfma_f32_16x16x32_bf16 v[122:125], v[166:169], v[194:197], v[122:125]
	v_mfma_f32_16x16x32_bf16 v[114:117], v[178:181], v[194:197], v[114:117]
	v_mfma_f32_16x16x32_bf16 v[114:117], v[170:173], v[190:193], v[114:117]
	v_mfma_f32_16x16x32_bf16 v[98:101], v[170:173], v[198:201], v[98:101]
	v_mfma_f32_16x16x32_bf16 v[98:101], v[178:181], v[202:205], v[98:101]
	v_mfma_f32_16x16x32_bf16 v[106:109], v[166:169], v[202:205], v[106:109]
	v_mfma_f32_16x16x32_bf16 v[106:109], v[162:165], v[198:201], v[106:109]
	v_mfma_f32_16x16x32_bf16 v[90:93], v[162:165], v[206:209], v[90:93]
	v_mfma_f32_16x16x32_bf16 v[90:93], v[166:169], v[228:231], v[90:93]
	v_mfma_f32_16x16x32_bf16 v[82:85], v[178:181], v[228:231], v[82:85]
	v_mfma_f32_16x16x32_bf16 v[82:85], v[170:173], v[206:209], v[82:85]
	v_mfma_f32_16x16x32_bf16 v[66:69], v[170:173], v[232:235], v[66:69]
	v_mfma_f32_16x16x32_bf16 v[66:69], v[178:181], v[236:239], v[66:69]
	v_mfma_f32_16x16x32_bf16 v[74:77], v[166:169], v[236:239], v[74:77]
	v_mfma_f32_16x16x32_bf16 v[74:77], v[162:165], v[232:235], v[74:77]
	s_setprio 0
	s_barrier
	s_add_i32 s22, s53, s26
	v_lshl_add_u64 v[140:141], v[140:141], 0, s[34:35]
	s_mov_b32 m0, s22
	ds_read_b128 v[190:193], v145 offset:49152
	ds_read_b128 v[194:197], v145 offset:50176
	ds_read_b128 v[198:201], v145 offset:51200
	ds_read_b128 v[202:205], v145 offset:52224
	ds_read_b128 v[206:209], v145 offset:53248
	ds_read_b128 v[228:231], v145 offset:54272
	ds_read_b128 v[232:235], v145 offset:55296
	ds_read_b128 v[236:239], v145 offset:56320
	global_load_lds_dwordx4 v[140:141], off
	s_add_i32 m0, s22, 0x2000
	s_add_u32 s18, s18, 0x100080
	v_lshl_add_u64 v[140:141], v[186:187], 0, s[34:35]
	s_addc_u32 s19, s19, 0
	s_add_i32 s22, s54, s26
	global_load_lds_dwordx4 v[140:141], off
	v_lshl_add_u64 v[140:141], s[18:19], 0, v[0:1]
	s_mov_b32 m0, s22
	s_nop 0
	global_load_lds_dwordx4 v[140:141], off
	v_lshl_add_u64 v[140:141], s[18:19], 0, v[130:131]
	s_add_i32 m0, s22, 0x2000
	s_nop 0
	global_load_lds_dwordx4 v[140:141], off
	v_lshl_add_u64 v[140:141], v[188:189], 0, s[34:35]
	s_mov_b32 m0, s43
	s_nop 0
	global_load_lds_dwordx4 v[140:141], off
	v_lshl_add_u64 v[140:141], v[210:211], 0, s[34:35]
	s_mov_b32 m0, s44
	s_nop 0
	global_load_lds_dwordx4 v[140:141], off
	s_waitcnt vmcnt(8)
	s_waitcnt lgkmcnt(0)
	s_barrier
	s_setprio 1
	s_waitcnt lgkmcnt(0)
	v_mfma_f32_16x16x32_bf16 v[62:65], v[146:149], v[190:193], v[62:65]
	v_mfma_f32_16x16x32_bf16 v[62:65], v[150:153], v[194:197], v[62:65]
	v_mfma_f32_16x16x32_bf16 v[54:57], v[158:161], v[194:197], v[54:57]
	v_mfma_f32_16x16x32_bf16 v[54:57], v[154:157], v[190:193], v[54:57]
	v_mfma_f32_16x16x32_bf16 v[38:41], v[154:157], v[198:201], v[38:41]
	v_mfma_f32_16x16x32_bf16 v[38:41], v[158:161], v[202:205], v[38:41]
	v_mfma_f32_16x16x32_bf16 v[46:49], v[150:153], v[202:205], v[46:49]
	v_mfma_f32_16x16x32_bf16 v[46:49], v[146:149], v[198:201], v[46:49]
	v_mfma_f32_16x16x32_bf16 v[30:33], v[146:149], v[206:209], v[30:33]
	v_mfma_f32_16x16x32_bf16 v[30:33], v[150:153], v[228:231], v[30:33]
	v_mfma_f32_16x16x32_bf16 v[22:25], v[158:161], v[228:231], v[22:25]
	v_mfma_f32_16x16x32_bf16 v[22:25], v[154:157], v[206:209], v[22:25]
	v_mfma_f32_16x16x32_bf16 v[6:9], v[154:157], v[232:235], v[6:9]
	v_mfma_f32_16x16x32_bf16 v[6:9], v[158:161], v[236:239], v[6:9]
	v_mfma_f32_16x16x32_bf16 v[14:17], v[150:153], v[236:239], v[14:17]
	v_mfma_f32_16x16x32_bf16 v[14:17], v[146:149], v[232:235], v[14:17]
	s_setprio 0
	s_setprio 1
	v_mfma_f32_16x16x32_bf16 v[58:61], v[162:165], v[190:193], v[58:61]
	v_mfma_f32_16x16x32_bf16 v[58:61], v[166:169], v[194:197], v[58:61]
	v_mfma_f32_16x16x32_bf16 v[50:53], v[178:181], v[194:197], v[50:53]
	v_mfma_f32_16x16x32_bf16 v[50:53], v[170:173], v[190:193], v[50:53]
	v_mfma_f32_16x16x32_bf16 v[34:37], v[170:173], v[198:201], v[34:37]
	v_mfma_f32_16x16x32_bf16 v[34:37], v[178:181], v[202:205], v[34:37]
	v_mfma_f32_16x16x32_bf16 v[42:45], v[166:169], v[202:205], v[42:45]
	v_mfma_f32_16x16x32_bf16 v[42:45], v[162:165], v[198:201], v[42:45]
	v_mfma_f32_16x16x32_bf16 v[26:29], v[162:165], v[206:209], v[26:29]
	v_mfma_f32_16x16x32_bf16 v[26:29], v[166:169], v[228:231], v[26:29]
	v_mfma_f32_16x16x32_bf16 v[18:21], v[178:181], v[228:231], v[18:21]
	v_mfma_f32_16x16x32_bf16 v[18:21], v[170:173], v[206:209], v[18:21]
	v_mfma_f32_16x16x32_bf16 v[2:5], v[170:173], v[232:235], v[2:5]
	v_mfma_f32_16x16x32_bf16 v[2:5], v[178:181], v[236:239], v[2:5]
	v_mfma_f32_16x16x32_bf16 v[10:13], v[166:169], v[236:239], v[10:13]
	v_mfma_f32_16x16x32_bf16 v[10:13], v[162:165], v[232:235], v[10:13]
	s_setprio 0
	s_barrier
	s_add_i32 s52, s52, 2
	s_add_u32 s16, s16, 0x100
	s_addc_u32 s17, s17, 0
	s_add_u32 s50, s50, 0x100
	s_addc_u32 s51, s51, 0
	s_cmp_gt_u32 s52, 61
	s_cbranch_scc0 .LBB0_721
	s_and_b64 vcc, exec, s[2:3]
	s_cbranch_vccz .LBB0_724
	s_barrier

.LBB0_805:
	s_add_u32 s16, s14, 0x100
	s_addc_u32 s17, s15, 0
	s_add_i32 s49, 0, 0x10000
	s_cmpk_eq_i32 s48, 0xa8
	s_cselect_b32 s23, s5, s17
	s_cselect_b32 s22, s4, s16
	v_add_u32_e32 v140, s49, v143
	s_cselect_b32 s19, s9, s47
	s_cselect_b32 s18, s8, s46
	s_add_i32 s50, 0, 0x14000
	ds_read_b128 v[146:149], v140
	ds_read_b128 v[150:153], v140 offset:1024
	ds_read_b128 v[154:157], v140 offset:2048
	ds_read_b128 v[158:161], v140 offset:3072
	v_add_u32_e32 v140, s50, v143
	ds_read_b128 v[162:165], v140
	ds_read_b128 v[166:169], v140 offset:1024
	ds_read_b128 v[170:173], v140 offset:2048
	ds_read_b128 v[178:181], v140 offset:3072
	v_lshl_add_u64 v[140:141], s[14:15], 0, v[136:137]
	s_add_i32 m0, s31, 0xc000
	ds_read_b128 v[190:193], v145
	ds_read_b128 v[194:197], v145 offset:1024
	ds_read_b128 v[198:201], v145 offset:2048
	ds_read_b128 v[202:205], v145 offset:3072
	ds_read_b128 v[206:209], v145 offset:4096
	ds_read_b128 v[228:231], v145 offset:5120
	ds_read_b128 v[232:235], v145 offset:6144
	ds_read_b128 v[236:239], v145 offset:7168
	global_load_lds_dwordx4 v[140:141], off
	v_lshl_add_u64 v[140:141], s[14:15], 0, v[138:139]
	s_add_i32 m0, s31, 0xe000
	s_nop 0
	global_load_lds_dwordx4 v[140:141], off
	s_waitcnt vmcnt(8)
	s_waitcnt lgkmcnt(0)
	s_barrier
	s_setprio 1
	s_waitcnt lgkmcnt(0)
	v_mfma_f32_16x16x32_bf16 v[126:129], v[146:149], v[190:193], v[126:129]
	v_mfma_f32_16x16x32_bf16 v[126:129], v[150:153], v[194:197], v[126:129]
	v_mfma_f32_16x16x32_bf16 v[122:125], v[158:161], v[194:197], v[122:125]
	v_mfma_f32_16x16x32_bf16 v[122:125], v[154:157], v[190:193], v[122:125]
	v_mfma_f32_16x16x32_bf16 v[110:113], v[154:157], v[198:201], v[110:113]
	v_mfma_f32_16x16x32_bf16 v[110:113], v[158:161], v[202:205], v[110:113]
	v_mfma_f32_16x16x32_bf16 v[118:121], v[150:153], v[202:205], v[118:121]
	v_mfma_f32_16x16x32_bf16 v[118:121], v[146:149], v[198:201], v[118:121]
	v_mfma_f32_16x16x32_bf16 v[102:105], v[146:149], v[206:209], v[102:105]
	v_mfma_f32_16x16x32_bf16 v[102:105], v[150:153], v[228:231], v[102:105]
	v_mfma_f32_16x16x32_bf16 v[94:97], v[158:161], v[228:231], v[94:97]
	v_mfma_f32_16x16x32_bf16 v[94:97], v[154:157], v[206:209], v[94:97]
	v_mfma_f32_16x16x32_bf16 v[78:81], v[154:157], v[232:235], v[78:81]
	v_mfma_f32_16x16x32_bf16 v[78:81], v[158:161], v[236:239], v[78:81]
	v_mfma_f32_16x16x32_bf16 v[86:89], v[150:153], v[236:239], v[86:89]
	v_mfma_f32_16x16x32_bf16 v[86:89], v[146:149], v[232:235], v[86:89]
	s_setprio 0
	s_setprio 1
	v_mfma_f32_16x16x32_bf16 v[114:117], v[162:165], v[190:193], v[114:117]
	v_mfma_f32_16x16x32_bf16 v[114:117], v[166:169], v[194:197], v[114:117]
	v_mfma_f32_16x16x32_bf16 v[106:109], v[178:181], v[194:197], v[106:109]
	v_mfma_f32_16x16x32_bf16 v[106:109], v[170:173], v[190:193], v[106:109]
	v_mfma_f32_16x16x32_bf16 v[90:93], v[170:173], v[198:201], v[90:93]
	v_mfma_f32_16x16x32_bf16 v[90:93], v[178:181], v[202:205], v[90:93]
	v_mfma_f32_16x16x32_bf16 v[98:101], v[166:169], v[202:205], v[98:101]
	v_mfma_f32_16x16x32_bf16 v[98:101], v[162:165], v[198:201], v[98:101]
	v_mfma_f32_16x16x32_bf16 v[82:85], v[162:165], v[206:209], v[82:85]
	v_mfma_f32_16x16x32_bf16 v[82:85], v[166:169], v[228:231], v[82:85]
	v_mfma_f32_16x16x32_bf16 v[74:77], v[178:181], v[228:231], v[74:77]
	v_mfma_f32_16x16x32_bf16 v[74:77], v[170:173], v[206:209], v[74:77]
	v_mfma_f32_16x16x32_bf16 v[66:69], v[170:173], v[232:235], v[66:69]
	v_mfma_f32_16x16x32_bf16 v[66:69], v[178:181], v[236:239], v[66:69]
	v_mfma_f32_16x16x32_bf16 v[70:73], v[166:169], v[236:239], v[70:73]
	v_mfma_f32_16x16x32_bf16 v[70:73], v[162:165], v[232:235], v[70:73]
	s_setprio 0
	s_barrier
	s_add_i32 s14, s49, s26
	v_lshl_add_u64 v[140:141], s[18:19], 0, v[0:1]
	s_mov_b32 m0, s14
	ds_read_b128 v[190:193], v145 offset:16384
	ds_read_b128 v[194:197], v145 offset:17408
	ds_read_b128 v[198:201], v145 offset:18432
	ds_read_b128 v[202:205], v145 offset:19456
	ds_read_b128 v[206:209], v145 offset:20480
	ds_read_b128 v[228:231], v145 offset:21504
	ds_read_b128 v[232:235], v145 offset:22528
	ds_read_b128 v[236:239], v145 offset:23552
	global_load_lds_dwordx4 v[140:141], off
	s_add_i32 m0, s14, 0x2000
	s_add_u32 s14, s18, 0x2b0000
	v_lshl_add_u64 v[186:187], s[18:19], 0, v[130:131]
	s_addc_u32 s15, s19, 0
	s_add_i32 s49, s50, s26
	global_load_lds_dwordx4 v[186:187], off
	v_lshl_add_u64 v[188:189], s[14:15], 0, v[0:1]
	s_mov_b32 m0, s49
	v_lshl_add_u64 v[210:211], s[22:23], 0, v[132:133]
	global_load_lds_dwordx4 v[188:189], off
	v_lshl_add_u64 v[188:189], s[14:15], 0, v[130:131]
	s_add_i32 m0, s49, 0x2000
	s_nop 0
	global_load_lds_dwordx4 v[188:189], off
	v_lshl_add_u64 v[188:189], s[22:23], 0, v[134:135]
	s_mov_b32 m0, s31
	s_nop 0
	global_load_lds_dwordx4 v[188:189], off
	s_mov_b32 m0, s36
	s_nop 0
	global_load_lds_dwordx4 v[210:211], off
	s_waitcnt vmcnt(8)
	s_waitcnt lgkmcnt(0)
	s_barrier
	s_setprio 1
	s_waitcnt lgkmcnt(0)
	v_mfma_f32_16x16x32_bf16 v[62:65], v[146:149], v[190:193], v[62:65]
	v_mfma_f32_16x16x32_bf16 v[62:65], v[150:153], v[194:197], v[62:65]
	v_mfma_f32_16x16x32_bf16 v[58:61], v[158:161], v[194:197], v[58:61]
	v_mfma_f32_16x16x32_bf16 v[58:61], v[154:157], v[190:193], v[58:61]
	v_mfma_f32_16x16x32_bf16 v[46:49], v[154:157], v[198:201], v[46:49]
	v_mfma_f32_16x16x32_bf16 v[46:49], v[158:161], v[202:205], v[46:49]
	v_mfma_f32_16x16x32_bf16 v[54:57], v[150:153], v[202:205], v[54:57]
	v_mfma_f32_16x16x32_bf16 v[54:57], v[146:149], v[198:201], v[54:57]
	v_mfma_f32_16x16x32_bf16 v[38:41], v[146:149], v[206:209], v[38:41]
	v_mfma_f32_16x16x32_bf16 v[38:41], v[150:153], v[228:231], v[38:41]
	v_mfma_f32_16x16x32_bf16 v[30:33], v[158:161], v[228:231], v[30:33]
	v_mfma_f32_16x16x32_bf16 v[30:33], v[154:157], v[206:209], v[30:33]
	v_mfma_f32_16x16x32_bf16 v[14:17], v[154:157], v[232:235], v[14:17]
	v_mfma_f32_16x16x32_bf16 v[14:17], v[158:161], v[236:239], v[14:17]
	v_mfma_f32_16x16x32_bf16 v[22:25], v[150:153], v[236:239], v[22:25]
	v_mfma_f32_16x16x32_bf16 v[22:25], v[146:149], v[232:235], v[22:25]
	s_setprio 0
	s_setprio 1
	v_mfma_f32_16x16x32_bf16 v[50:53], v[162:165], v[190:193], v[50:53]
	v_mfma_f32_16x16x32_bf16 v[50:53], v[166:169], v[194:197], v[50:53]
	v_mfma_f32_16x16x32_bf16 v[42:45], v[178:181], v[194:197], v[42:45]
	v_mfma_f32_16x16x32_bf16 v[42:45], v[170:173], v[190:193], v[42:45]
	v_mfma_f32_16x16x32_bf16 v[26:29], v[170:173], v[198:201], v[26:29]
	v_mfma_f32_16x16x32_bf16 v[26:29], v[178:181], v[202:205], v[26:29]
	v_mfma_f32_16x16x32_bf16 v[34:37], v[166:169], v[202:205], v[34:37]
	v_mfma_f32_16x16x32_bf16 v[34:37], v[162:165], v[198:201], v[34:37]
	v_mfma_f32_16x16x32_bf16 v[18:21], v[162:165], v[206:209], v[18:21]
	v_mfma_f32_16x16x32_bf16 v[18:21], v[166:169], v[228:231], v[18:21]
	v_mfma_f32_16x16x32_bf16 v[10:13], v[178:181], v[228:231], v[10:13]
	v_mfma_f32_16x16x32_bf16 v[10:13], v[170:173], v[206:209], v[10:13]
	v_mfma_f32_16x16x32_bf16 v[2:5], v[170:173], v[232:235], v[2:5]
	v_mfma_f32_16x16x32_bf16 v[2:5], v[178:181], v[236:239], v[2:5]
	v_mfma_f32_16x16x32_bf16 v[6:9], v[166:169], v[236:239], v[6:9]
	v_mfma_f32_16x16x32_bf16 v[6:9], v[162:165], v[232:235], v[6:9]
	s_setprio 0
	s_barrier
	s_add_i32 s49, 0, 0x18000
	s_add_i32 s50, 0, 0x1c000
	v_add_u32_e32 v158, s49, v143
	v_add_u32_e32 v175, s50, v143
	ds_read_b128 v[146:149], v158
	ds_read_b128 v[150:153], v158 offset:1024
	ds_read_b128 v[154:157], v158 offset:2048
	ds_read_b128 v[158:161], v158 offset:3072
	ds_read_b128 v[162:165], v175
	ds_read_b128 v[166:169], v175 offset:1024
	ds_read_b128 v[170:173], v175 offset:2048
	ds_read_b128 v[178:181], v175 offset:3072
	s_add_u32 s14, s22, 0x2b0000
	s_addc_u32 s15, s23, 0
	s_mov_b32 m0, s37
	v_lshl_add_u64 v[226:227], s[14:15], 0, v[134:135]
	ds_read_b128 v[190:193], v145 offset:32768
	ds_read_b128 v[194:197], v145 offset:33792
	ds_read_b128 v[198:201], v145 offset:34816
	ds_read_b128 v[202:205], v145 offset:35840
	ds_read_b128 v[206:209], v145 offset:36864
	ds_read_b128 v[228:231], v145 offset:37888
	ds_read_b128 v[232:235], v145 offset:38912
	ds_read_b128 v[236:239], v145 offset:39936
	global_load_lds_dwordx4 v[226:227], off
	v_lshl_add_u64 v[226:227], s[14:15], 0, v[132:133]
	s_mov_b32 m0, s38
	s_nop 0
	global_load_lds_dwordx4 v[226:227], off
	s_waitcnt vmcnt(8)
	s_waitcnt lgkmcnt(0)
	s_barrier
	s_setprio 1
	s_waitcnt lgkmcnt(0)
	v_mfma_f32_16x16x32_bf16 v[126:129], v[146:149], v[190:193], v[126:129]
	v_mfma_f32_16x16x32_bf16 v[126:129], v[150:153], v[194:197], v[126:129]
	v_mfma_f32_16x16x32_bf16 v[122:125], v[158:161], v[194:197], v[122:125]
	v_mfma_f32_16x16x32_bf16 v[122:125], v[154:157], v[190:193], v[122:125]
	v_mfma_f32_16x16x32_bf16 v[110:113], v[154:157], v[198:201], v[110:113]
	v_mfma_f32_16x16x32_bf16 v[110:113], v[158:161], v[202:205], v[110:113]
	v_mfma_f32_16x16x32_bf16 v[118:121], v[150:153], v[202:205], v[118:121]
	v_mfma_f32_16x16x32_bf16 v[118:121], v[146:149], v[198:201], v[118:121]
	v_mfma_f32_16x16x32_bf16 v[102:105], v[146:149], v[206:209], v[102:105]
	v_mfma_f32_16x16x32_bf16 v[102:105], v[150:153], v[228:231], v[102:105]
	v_mfma_f32_16x16x32_bf16 v[94:97], v[158:161], v[228:231], v[94:97]
	v_mfma_f32_16x16x32_bf16 v[94:97], v[154:157], v[206:209], v[94:97]
	v_mfma_f32_16x16x32_bf16 v[78:81], v[154:157], v[232:235], v[78:81]
	v_mfma_f32_16x16x32_bf16 v[78:81], v[158:161], v[236:239], v[78:81]
	v_mfma_f32_16x16x32_bf16 v[86:89], v[150:153], v[236:239], v[86:89]
	v_mfma_f32_16x16x32_bf16 v[86:89], v[146:149], v[232:235], v[86:89]
	s_setprio 0
	s_setprio 1
	v_mfma_f32_16x16x32_bf16 v[114:117], v[162:165], v[190:193], v[114:117]
	v_mfma_f32_16x16x32_bf16 v[114:117], v[166:169], v[194:197], v[114:117]
	v_mfma_f32_16x16x32_bf16 v[106:109], v[178:181], v[194:197], v[106:109]
	v_mfma_f32_16x16x32_bf16 v[106:109], v[170:173], v[190:193], v[106:109]
	v_mfma_f32_16x16x32_bf16 v[90:93], v[170:173], v[198:201], v[90:93]
	v_mfma_f32_16x16x32_bf16 v[90:93], v[178:181], v[202:205], v[90:93]
	v_mfma_f32_16x16x32_bf16 v[98:101], v[166:169], v[202:205], v[98:101]
	v_mfma_f32_16x16x32_bf16 v[98:101], v[162:165], v[198:201], v[98:101]
	v_mfma_f32_16x16x32_bf16 v[82:85], v[162:165], v[206:209], v[82:85]
	v_mfma_f32_16x16x32_bf16 v[82:85], v[166:169], v[228:231], v[82:85]
	v_mfma_f32_16x16x32_bf16 v[74:77], v[178:181], v[228:231], v[74:77]
	v_mfma_f32_16x16x32_bf16 v[74:77], v[170:173], v[206:209], v[74:77]
	v_mfma_f32_16x16x32_bf16 v[66:69], v[170:173], v[232:235], v[66:69]
	v_mfma_f32_16x16x32_bf16 v[66:69], v[178:181], v[236:239], v[66:69]
	v_mfma_f32_16x16x32_bf16 v[70:73], v[166:169], v[236:239], v[70:73]
	v_mfma_f32_16x16x32_bf16 v[70:73], v[162:165], v[232:235], v[70:73]
	s_setprio 0
	s_barrier
	s_add_i32 s14, s49, s26
	v_lshl_add_u64 v[140:141], v[140:141], 0, s[34:35]
	s_mov_b32 m0, s14
	ds_read_b128 v[190:193], v145 offset:49152
	ds_read_b128 v[194:197], v145 offset:50176
	ds_read_b128 v[198:201], v145 offset:51200
	ds_read_b128 v[202:205], v145 offset:52224
	ds_read_b128 v[206:209], v145 offset:53248
	ds_read_b128 v[228:231], v145 offset:54272
	ds_read_b128 v[232:235], v145 offset:55296
	ds_read_b128 v[236:239], v145 offset:56320
	global_load_lds_dwordx4 v[140:141], off
	s_add_i32 m0, s14, 0x2000
	s_add_u32 s14, s18, 0x2b0080
	v_lshl_add_u64 v[140:141], v[186:187], 0, s[34:35]
	s_addc_u32 s15, s19, 0
	s_add_i32 s18, s50, s26
	global_load_lds_dwordx4 v[140:141], off
	v_lshl_add_u64 v[140:141], s[14:15], 0, v[0:1]
	s_mov_b32 m0, s18
	s_nop 0
	global_load_lds_dwordx4 v[140:141], off
	v_lshl_add_u64 v[140:141], s[14:15], 0, v[130:131]
	s_add_i32 m0, s18, 0x2000
	s_nop 0
	global_load_lds_dwordx4 v[140:141], off
	v_lshl_add_u64 v[140:141], v[188:189], 0, s[34:35]
	s_mov_b32 m0, s39
	s_nop 0
	global_load_lds_dwordx4 v[140:141], off
	v_lshl_add_u64 v[140:141], v[210:211], 0, s[34:35]
	s_mov_b32 m0, s40
	s_nop 0
	global_load_lds_dwordx4 v[140:141], off
	s_waitcnt vmcnt(8)
	s_waitcnt lgkmcnt(0)
	s_barrier
	s_setprio 1
	s_waitcnt lgkmcnt(0)
	v_mfma_f32_16x16x32_bf16 v[62:65], v[146:149], v[190:193], v[62:65]
	v_mfma_f32_16x16x32_bf16 v[62:65], v[150:153], v[194:197], v[62:65]
	v_mfma_f32_16x16x32_bf16 v[58:61], v[158:161], v[194:197], v[58:61]
	v_mfma_f32_16x16x32_bf16 v[58:61], v[154:157], v[190:193], v[58:61]
	v_mfma_f32_16x16x32_bf16 v[46:49], v[154:157], v[198:201], v[46:49]
	v_mfma_f32_16x16x32_bf16 v[46:49], v[158:161], v[202:205], v[46:49]
	v_mfma_f32_16x16x32_bf16 v[54:57], v[150:153], v[202:205], v[54:57]
	v_mfma_f32_16x16x32_bf16 v[54:57], v[146:149], v[198:201], v[54:57]
	v_mfma_f32_16x16x32_bf16 v[38:41], v[146:149], v[206:209], v[38:41]
	v_mfma_f32_16x16x32_bf16 v[38:41], v[150:153], v[228:231], v[38:41]
	v_mfma_f32_16x16x32_bf16 v[30:33], v[158:161], v[228:231], v[30:33]
	v_mfma_f32_16x16x32_bf16 v[30:33], v[154:157], v[206:209], v[30:33]
	v_mfma_f32_16x16x32_bf16 v[14:17], v[154:157], v[232:235], v[14:17]
	v_mfma_f32_16x16x32_bf16 v[14:17], v[158:161], v[236:239], v[14:17]
	v_mfma_f32_16x16x32_bf16 v[22:25], v[150:153], v[236:239], v[22:25]
	v_mfma_f32_16x16x32_bf16 v[22:25], v[146:149], v[232:235], v[22:25]
	s_setprio 0
	s_setprio 1
	v_mfma_f32_16x16x32_bf16 v[50:53], v[162:165], v[190:193], v[50:53]
	v_mfma_f32_16x16x32_bf16 v[50:53], v[166:169], v[194:197], v[50:53]
	v_mfma_f32_16x16x32_bf16 v[42:45], v[178:181], v[194:197], v[42:45]
	v_mfma_f32_16x16x32_bf16 v[42:45], v[170:173], v[190:193], v[42:45]
	v_mfma_f32_16x16x32_bf16 v[26:29], v[170:173], v[198:201], v[26:29]
	v_mfma_f32_16x16x32_bf16 v[26:29], v[178:181], v[202:205], v[26:29]
	v_mfma_f32_16x16x32_bf16 v[34:37], v[166:169], v[202:205], v[34:37]
	v_mfma_f32_16x16x32_bf16 v[34:37], v[162:165], v[198:201], v[34:37]
	v_mfma_f32_16x16x32_bf16 v[18:21], v[162:165], v[206:209], v[18:21]
	v_mfma_f32_16x16x32_bf16 v[18:21], v[166:169], v[228:231], v[18:21]
	v_mfma_f32_16x16x32_bf16 v[10:13], v[178:181], v[228:231], v[10:13]
	v_mfma_f32_16x16x32_bf16 v[10:13], v[170:173], v[206:209], v[10:13]
	v_mfma_f32_16x16x32_bf16 v[2:5], v[170:173], v[232:235], v[2:5]
	v_mfma_f32_16x16x32_bf16 v[2:5], v[178:181], v[236:239], v[2:5]
	v_mfma_f32_16x16x32_bf16 v[6:9], v[166:169], v[236:239], v[6:9]
	v_mfma_f32_16x16x32_bf16 v[6:9], v[162:165], v[232:235], v[6:9]
	s_setprio 0
	s_barrier
	s_add_i32 s48, s48, 2
	s_add_u32 s46, s46, 0x100
	s_addc_u32 s47, s47, 0
	s_cmpk_gt_u32 s48, 0xa9
	s_mov_b64 s[14:15], s[16:17]
	s_cbranch_scc0 .LBB0_805
	s_and_b64 vcc, exec, s[6:7]
	s_cbranch_vccz .LBB0_808
	s_barrier
